# mLSTM H stores: 4x dwordx2 -> 2x dwordx4 per lane via v_permlane32_swap between the hh halves
# speedup vs baseline: 1.0092x; 1.0092x over previous
; #define LAS __attribute__((address_space(3)))
; #define MFMA32(a, b, c) __builtin_amdgcn_mfma_f32_32x32x16_bf16((a), (b), (c), 0, 0, 0)
; DI float lo_f(unsigned u) { return __uint_as_float(u << 16); }
; DI float hi_f(unsigned u) { return __uint_as_float(u & 0xffff0000u); }
; DI float bf2f(unsigned short b) { return __uint_as_float((unsigned)b << 16); }
; DI void mlstm_seq(LAS unsigned char* lds, const bf16* P, const float* IFg, bf16* Hout, const float* conv_w, const float* conv_b, const float* mlg, int seq) {
;     ...
;         for (int i = 0; i < 16; ++i) Cst[i] *= dec;
; #pragma unroll
;         for (int k4 = 0; k4 < 4; ++k4) { const f32x4 wa = *(const LAS f32x4*)(gate + 256 + 16 * k4 + 4 * hh), wb = *(const LAS f32x4*)(gate + 256 + 16 * k4 + 8 + 4 * hh);
;             LAS unsigned char* p = Kt2 + (16 * k4 + 4 * hh + q4) * 192 + 2 * (32 * th + 16 * gg + 4 * p4); const v4u kq = __builtin_bit_cast(v4u, tr8(p, p + 8 * 192));
;             const bf16x8 kf2 = pack8(lo_f(kq.x) * wa[0], hi_f(kq.x) * wa[1], lo_f(kq.y) * wa[2], hi_f(kq.y) * wa[3], lo_f(kq.z) * wb[0], hi_f(kq.z) * wb[1], lo_f(kq.w) * wb[2], hi_f(kq.w) * wb[3]);
;             Cst = MFMA32(vf[k4], kf2, Cst); }
;         { float np = 0.f;
; #pragma unroll
;             for (int i = 0; i < 8; ++i) { const int s = 8 * wv + i; np += gate[256 + s] * bf2f(*(const LAS unsigned short*)(Kt + s * 144 + 2 * lane)); }
;             npart[wv * 64 + lane] = np; }
;         __syncthreads();
.LBB0_383:
	s_or_b64 exec, exec, s[20:21]
	s_waitcnt lgkmcnt(0)
	ds_read_b128 v[2:5], v215
	ds_read_b128 v[6:9], v216
	ds_read_b64_tr_b16 v[10:11], v227 offset:18432
	ds_read_b64_tr_b16 v[12:13], v227 offset:19968
	v_pk_mul_f32 v[30:31], v[30:31], v[144:145] op_sel_hi:[1,0]
	v_pk_mul_f32 v[28:29], v[28:29], v[144:145] op_sel_hi:[1,0]
	v_pk_mul_f32 v[26:27], v[26:27], v[144:145] op_sel_hi:[1,0]
	s_waitcnt lgkmcnt(1)
	v_lshlrev_b32_e32 v32, 16, v10
	v_and_b32_e32 v10, 0xffff0000, v10
	v_mul_f32_e32 v3, v3, v10
	v_lshlrev_b32_e32 v10, 16, v11
	v_mul_f32_e32 v4, v4, v10
	v_and_b32_e32 v10, 0xffff0000, v11
	v_mul_f32_e32 v5, v5, v10
	s_waitcnt lgkmcnt(0)
	v_lshlrev_b32_e32 v10, 16, v12
	v_mul_f32_e32 v6, v6, v10
	v_and_b32_e32 v10, 0xffff0000, v12
	v_mul_f32_e32 v7, v7, v10
	v_lshlrev_b32_e32 v10, 16, v13
	v_mul_f32_e32 v8, v8, v10
	v_and_b32_e32 v10, 0xffff0000, v13
	v_mul_f32_e32 v2, v2, v32
	v_mul_f32_e32 v9, v9, v10
	v_cvt_pk_bf16_f32 v2, v2, v3
	v_cvt_pk_bf16_f32 v3, v4, v5
	v_cvt_pk_bf16_f32 v4, v6, v7
	v_cvt_pk_bf16_f32 v5, v8, v9
	ds_read_b128 v[6:9], v217
	ds_read_b128 v[10:13], v218
	ds_read_b64_tr_b16 v[32:33], v227 offset:21504
	ds_read_b64_tr_b16 v[34:35], v227 offset:23040
	v_pk_mul_f32 v[24:25], v[24:25], v[144:145] op_sel_hi:[1,0]
	v_pk_mul_f32 v[22:23], v[22:23], v[144:145] op_sel_hi:[1,0]
	v_pk_mul_f32 v[20:21], v[20:21], v[144:145] op_sel_hi:[1,0]
	s_waitcnt lgkmcnt(1)
	v_lshlrev_b32_e32 v44, 16, v32
	v_and_b32_e32 v32, 0xffff0000, v32
	v_mul_f32_e32 v7, v7, v32
	v_lshlrev_b32_e32 v32, 16, v33
	v_mul_f32_e32 v8, v8, v32
	v_and_b32_e32 v32, 0xffff0000, v33
	v_mul_f32_e32 v9, v9, v32
	s_waitcnt lgkmcnt(0)
	v_lshlrev_b32_e32 v32, 16, v34
	v_mul_f32_e32 v10, v10, v32
	v_and_b32_e32 v32, 0xffff0000, v34
	v_mul_f32_e32 v11, v11, v32
	v_lshlrev_b32_e32 v32, 16, v35
	v_mul_f32_e32 v12, v12, v32
	v_and_b32_e32 v32, 0xffff0000, v35
	v_mul_f32_e32 v6, v6, v44
	v_mul_f32_e32 v13, v13, v32
	v_cvt_pk_bf16_f32 v6, v6, v7
	v_cvt_pk_bf16_f32 v7, v8, v9
	v_cvt_pk_bf16_f32 v8, v10, v11
	v_cvt_pk_bf16_f32 v9, v12, v13
	ds_read_b128 v[10:13], v219
	ds_read_b128 v[32:35], v220
	ds_read_b64_tr_b16 v[44:45], v228 offset:18432
	ds_read_b64_tr_b16 v[46:47], v228 offset:19968
	v_pk_mul_f32 v[18:19], v[18:19], v[144:145] op_sel_hi:[1,0]
	v_pk_mul_f32 v[16:17], v[16:17], v[144:145] op_sel_hi:[1,0]
	s_mov_b32 s20, 0x800000
	s_waitcnt lgkmcnt(1)
	v_lshlrev_b32_e32 v53, 16, v44
	v_and_b32_e32 v44, 0xffff0000, v44
	v_mul_f32_e32 v11, v11, v44
	v_lshlrev_b32_e32 v44, 16, v45
	v_mul_f32_e32 v12, v12, v44
	v_and_b32_e32 v44, 0xffff0000, v45
	v_mul_f32_e32 v13, v13, v44
	s_waitcnt lgkmcnt(0)
	v_lshlrev_b32_e32 v44, 16, v46
	v_mul_f32_e32 v32, v32, v44
	v_and_b32_e32 v44, 0xffff0000, v46
	v_mul_f32_e32 v33, v33, v44
	v_lshlrev_b32_e32 v44, 16, v47
	v_mul_f32_e32 v34, v34, v44
	v_and_b32_e32 v44, 0xffff0000, v47
	v_mul_f32_e32 v10, v10, v53
	v_mul_f32_e32 v35, v35, v44
	v_cvt_pk_bf16_f32 v10, v10, v11
	v_cvt_pk_bf16_f32 v11, v12, v13
	v_cvt_pk_bf16_f32 v12, v32, v33
	v_cvt_pk_bf16_f32 v13, v34, v35
	ds_read_b128 v[32:35], v221
	ds_read_b128 v[44:47], v222
	ds_read_b64_tr_b16 v[54:55], v227 offset:27648
	ds_read_b64_tr_b16 v[56:57], v227 offset:29184
	v_mfma_f32_32x32x16_bf16 v[16:31], v[120:123], v[2:5], v[16:31]
	s_waitcnt lgkmcnt(1)
	v_lshlrev_b32_e32 v53, 16, v54
	v_mul_f32_e32 v32, v32, v53
	v_and_b32_e32 v53, 0xffff0000, v54
	v_mul_f32_e32 v33, v33, v53
	v_lshlrev_b32_e32 v53, 16, v55
	v_mul_f32_e32 v34, v34, v53
	v_and_b32_e32 v53, 0xffff0000, v55
	v_mul_f32_e32 v35, v35, v53
	s_waitcnt lgkmcnt(0)
	v_lshlrev_b32_e32 v53, 16, v56
	v_mul_f32_e32 v44, v44, v53
	v_and_b32_e32 v53, 0xffff0000, v56
	v_mul_f32_e32 v45, v45, v53
	v_lshlrev_b32_e32 v53, 16, v57
	v_mul_f32_e32 v46, v46, v53
	v_and_b32_e32 v53, 0xffff0000, v57
	v_mul_f32_e32 v47, v47, v53
	v_cvt_pk_bf16_f32 v32, v32, v33
	v_cvt_pk_bf16_f32 v33, v34, v35
	v_cvt_pk_bf16_f32 v34, v44, v45
	v_mov_b32_e32 v44, s33
	v_cvt_pk_bf16_f32 v35, v46, v47
	v_add_u32_e32 v53, s27, v210
	ds_read_b128 v[44:47], v44 offset:1024
	ds_read_u16 v54, v53 offset:9216
	ds_read_u16 v55, v53 offset:9360
	v_add_u32_e32 v56, s88, v210
	v_mfma_f32_32x32x16_bf16 v[16:31], v[108:111], v[6:9], v[16:31]
	s_waitcnt lgkmcnt(1)
	v_lshlrev_b32_e32 v54, 16, v54
	s_waitcnt lgkmcnt(0)
	v_lshlrev_b32_e32 v55, 16, v55
	v_mul_f32_e64 v44, v44, v54
	v_mul_f32_e64 v45, v45, v55
	v_add_f32_e32 v44, 0, v44
	v_add_f32_e32 v54, v44, v45
	ds_read_u16 v44, v56 offset:9216
	ds_read_u16 v45, v53 offset:9648
	v_mfma_f32_32x32x16_bf16 v[16:31], v[116:119], v[10:13], v[16:31]
	s_waitcnt lgkmcnt(1)
	v_lshlrev_b32_e32 v44, 16, v44
	s_waitcnt lgkmcnt(0)
	v_lshlrev_b32_e32 v45, 16, v45
	v_mul_f32_e64 v44, v46, v44
	v_mul_f32_e64 v45, v47, v45
	v_add_f32_e32 v44, v54, v44
	v_add_f32_e32 v57, v44, v45
	v_mov_b32_e32 v44, s26
	ds_read_b128 v[44:47], v44 offset:1024
	ds_read_u16 v54, v56 offset:9504
	ds_read_u16 v55, v53 offset:9936
	v_mfma_f32_32x32x16_bf16 v[16:31], v[112:115], v[32:35], v[16:31]
	s_waitcnt lgkmcnt(1)
	v_lshlrev_b32_e32 v54, 16, v54
	s_waitcnt lgkmcnt(0)
	v_lshlrev_b32_e32 v55, 16, v55
	v_mul_f32_e64 v44, v44, v54
	v_mul_f32_e64 v45, v45, v55
	v_add_f32_e32 v44, v57, v44
	v_add_f32_e32 v54, v44, v45
	ds_read_u16 v44, v56 offset:9792
	ds_read_u16 v45, v53 offset:10224
	s_waitcnt lgkmcnt(1)
	v_lshlrev_b32_e32 v44, 16, v44
	s_waitcnt lgkmcnt(0)
	v_lshlrev_b32_e32 v45, 16, v45
	v_pk_mul_f32 v[44:45], v[46:47], v[44:45]
	s_nop 0
	v_add_f32_e32 v44, v54, v44
	v_add_f32_e32 v44, v44, v45
	ds_write_b32 v185, v44
	s_waitcnt lgkmcnt(0)
	s_barrier
; #define LAS __attribute__((address_space(3)))
; DI float lo_f(unsigned u) { return __uint_as_float(u << 16); }
; DI float hi_f(unsigned u) { return __uint_as_float(u & 0xffff0000u); }
; DI unsigned pk2(float lo, float hi) { return pg8::cvt_pk_bf16(lo, hi); }
; DI void mlstm_seq(LAS unsigned char* lds, const bf16* P, const float* IFg, bf16* Hout, const float* conv_w, const float* conv_b, const float* mlg, int seq) {
;     ...
;         const float tot = ssq[t] + ssq[64 + t] + ssq[128 + t] + ssq[192 + t]; const float rstd = rsqrtf(tot * (1.0f / 128.0f) + 1e-6f);
; #pragma unroll
;         for (int rq = 0; rq < 4; ++rq) { const int dv = 32 * dvs + 8 * rq + 4 * hh; const f32x4 gl = *(const LAS f32x4*)(mlgl + dv);
;             const float o0 = hv[4 * rq] * rstd * gl[0] * lo_f(og[rq].x), o1 = hv[4 * rq + 1] * rstd * gl[1] * hi_f(og[rq].x), o2 = hv[4 * rq + 2] * rstd * gl[2] * lo_f(og[rq].y), o3 = hv[4 * rq + 3] * rstd * gl[3] * hi_f(og[rq].y);
;             v2u w; w.x = pk2(o0, o1); w.y = pk2(o2, o3); *(v2u*)(Hout + row * 1024 + hd * 128 + dv) = w;
;             v2u cw; cw.x = pk2(Cst[4 * rq], Cst[4 * rq + 1]); cw.y = pk2(Cst[4 * rq + 2], Cst[4 * rq + 3]);
;             *(LAS v2u*)(Cimg + (32 * th + r32) * 320 + 2 * dv) = cw; }
	ds_read_b32 v2, v209
	ds_read_b32 v3, v211
	s_waitcnt lgkmcnt(0)
	v_add_f32_e32 v2, v2, v3
	ds_read_b32 v3, v212
	s_waitcnt lgkmcnt(0)
	v_add_f32_e32 v2, v2, v3
	ds_read_b32 v3, v213
	s_waitcnt lgkmcnt(0)
	v_add_f32_e32 v2, v2, v3
	v_fmamk_f32 v2, v2, 0x3c000000, v192
	v_cmp_gt_f32_e32 vcc, s20, v2
	v_mul_f32_e32 v3, 0x4b800000, v2
	v_readlane_b32 s20, v251, 8
	v_cndmask_b32_e32 v2, v2, v3, vcc
	v_rsq_f32_e32 v2, v2
	v_readlane_b32 s21, v251, 9
	v_readlane_b32 s22, v251, 10
	v_readlane_b32 s23, v251, 11
	v_mul_f32_e32 v3, 0x45800000, v2
	v_cndmask_b32_e32 v8, v2, v3, vcc
	v_lshl_add_u64 v[6:7], s[20:21], 0, v[136:137]
	s_andn2_b64 vcc, exec, s[86:87]
	v_lshrrev_b32_e32 v4, 5, v194
	v_mul_u32_u24_e32 v4, 24, v4
	v_mov_b32_e32 v5, 0
	v_lshl_add_u64 v[6:7], v[6:7], 0, v[4:5]
	s_waitcnt vmcnt(0)
	ds_read_b128 v[2:5], v204
	v_mul_f32_e32 v0, v0, v8
	s_waitcnt lgkmcnt(0)
	v_mul_f32_e32 v0, v2, v0
	v_lshlrev_b32_e32 v2, 16, v152
	v_mul_f32_e32 v0, v0, v2
	v_mul_f32_e32 v2, v14, v8
	v_mul_f32_e32 v2, v3, v2
	v_and_b32_e32 v3, 0xffff0000, v152
	v_mul_f32_e32 v2, v2, v3
	v_mul_f32_e32 v3, v48, v8
	v_mul_f32_e32 v3, v4, v3
	v_lshlrev_b32_e32 v4, 16, v153
	v_mul_f32_e32 v3, v3, v4
	v_mul_f32_e32 v4, v49, v8
	v_mul_f32_e32 v4, v5, v4
	v_and_b32_e32 v5, 0xffff0000, v153
	v_mul_f32_e32 v4, v4, v5
	v_cvt_pk_bf16_f32 v152, v0, v2
	v_cvt_pk_bf16_f32 v153, v3, v4
	v_add_u32_e32 v0, v140, v208
	v_cvt_pk_bf16_f32 v2, v16, v17
	v_cvt_pk_bf16_f32 v3, v18, v19
	ds_write_b64 v0, v[2:3] offset:51200
	ds_read_b128 v[2:5], v206
	v_mul_f32_e32 v0, v40, v8
	s_waitcnt lgkmcnt(0)
	v_mul_f32_e32 v0, v2, v0
	v_lshlrev_b32_e32 v2, 16, v148
	v_mul_f32_e32 v0, v0, v2
	v_mul_f32_e32 v2, v41, v8
	v_mul_f32_e32 v2, v3, v2
	v_and_b32_e32 v3, 0xffff0000, v148
	v_mul_f32_e32 v2, v2, v3
	v_mul_f32_e32 v3, v42, v8
	v_mul_f32_e32 v3, v4, v3
	v_lshlrev_b32_e32 v4, 16, v149
	v_mul_f32_e32 v3, v3, v4
	v_mul_f32_e32 v4, v43, v8
	v_mul_f32_e32 v4, v5, v4
	v_and_b32_e32 v5, 0xffff0000, v149
	v_mul_f32_e32 v4, v4, v5
	v_cvt_pk_bf16_f32 v42, v0, v2
	v_cvt_pk_bf16_f32 v43, v3, v4
	v_mov_b32_e32 v40, v152
	v_mov_b32_e32 v41, v153
	v_cvt_pk_bf16_f32 v2, v20, v21
	v_cvt_pk_bf16_f32 v3, v22, v23
	ds_write_b64 v229, v[2:3] offset:51200
	ds_read_b128 v[2:5], v207
	v_mul_f32_e32 v0, v36, v8
	s_waitcnt lgkmcnt(0)
	v_mul_f32_e32 v0, v2, v0
	v_lshlrev_b32_e32 v2, 16, v146
	v_mul_f32_e32 v0, v0, v2
	v_mul_f32_e32 v2, v37, v8
	v_mul_f32_e32 v2, v3, v2
	v_and_b32_e32 v3, 0xffff0000, v146
	v_mul_f32_e32 v2, v2, v3
	v_mul_f32_e32 v3, v38, v8
	v_mul_f32_e32 v3, v4, v3
	v_lshlrev_b32_e32 v4, 16, v147
	v_mul_f32_e32 v3, v3, v4
	v_mul_f32_e32 v4, v39, v8
	v_mul_f32_e32 v4, v5, v4
	v_and_b32_e32 v5, 0xffff0000, v147
	v_mul_f32_e32 v4, v4, v5
	v_cvt_pk_bf16_f32 v38, v0, v2
	v_cvt_pk_bf16_f32 v39, v3, v4
	v_cvt_pk_bf16_f32 v2, v24, v25
	v_cvt_pk_bf16_f32 v3, v26, v27
	ds_write_b64 v230, v[2:3] offset:51200
	ds_read_b128 v[2:5], v205
	v_mul_f32_e32 v0, v15, v8
	s_waitcnt lgkmcnt(0)
	v_mul_f32_e32 v0, v2, v0
	v_lshlrev_b32_e32 v2, 16, v150
	v_mul_f32_e32 v0, v0, v2
	v_mul_f32_e32 v2, v50, v8
	v_mul_f32_e32 v2, v3, v2
	v_and_b32_e32 v3, 0xffff0000, v150
	v_mul_f32_e32 v2, v2, v3
	v_mul_f32_e32 v3, v51, v8
	v_mul_f32_e32 v3, v4, v3
	v_lshlrev_b32_e32 v4, 16, v151
	v_mul_f32_e32 v3, v3, v4
	v_mul_f32_e32 v4, v52, v8
	v_mul_f32_e32 v4, v5, v4
	v_and_b32_e32 v5, 0xffff0000, v151
	v_mul_f32_e32 v4, v4, v5
	v_cvt_pk_bf16_f32 v36, v0, v2
	v_cvt_pk_bf16_f32 v37, v3, v4
	v_cvt_pk_bf16_f32 v2, v28, v29
	v_cvt_pk_bf16_f32 v3, v30, v31
	ds_write_b64 v231, v[2:3] offset:51200
	s_nop 1
	v_permlane32_swap_b32_e32 v40, v42
	v_permlane32_swap_b32_e32 v41, v43
	v_permlane32_swap_b32_e32 v36, v38
	v_permlane32_swap_b32_e32 v37, v39
	global_store_dwordx4 v[6:7], v[40:43], off offset:-32
	global_store_dwordx4 v[6:7], v[36:39], off offset:-16
	s_cbranch_vccnz .LBB0_385
	ds_read2st64_b32 v[2:3], v184 offset1:1
	s_waitcnt lgkmcnt(0)
	v_add_f32_e32 v0, 0, v2
	v_add_f32_e32 v0, v0, v3
	ds_read2st64_b32 v[2:3], v184 offset0:2 offset1:3
	s_waitcnt lgkmcnt(0)
	v_add_f32_e32 v0, v0, v2
	v_add_f32_e32 v0, v0, v3
	ds_read2st64_b32 v[2:3], v184 offset0:4 offset1:5
	s_waitcnt lgkmcnt(0)
	v_add_f32_e32 v0, v0, v2
	v_add_f32_e32 v0, v0, v3
	ds_read2st64_b32 v[2:3], v184 offset0:6 offset1:7
	s_waitcnt lgkmcnt(0)
	v_add_f32_e32 v0, v0, v2
	v_add_f32_e32 v0, v0, v3
	v_fmac_f32_e32 v0, v223, v144
	v_mov_b32_e32 v223, v0
	ds_write_b32 v186, v0
